# helper allocation refined: layer-1 w_ffn_down converted in the idle tail of layer-1 gate/up GEMM, layer-0 w_ffn_down in layer-0 out-proj / gate-up tails
# speedup vs baseline: 1.0005x; 1.0005x over previous
.LBB0_115:
	s_or_b64 exec, exec, s[2:3]
	s_abs_i32 s15, s12
	v_cvt_f32_u32_e32 v2, s15
	v_lshlrev_b32_e32 v0, 2, v76
	v_and_b32_e32 v82, 60, v0
	s_sub_i32 s2, 0, s15
	v_rcp_iflag_f32_e32 v0, v2
	s_mov_b32 s13, s88
	s_add_i32 s14, s13, s12
	v_mul_f32_e32 v0, 0x4f7ffffe, v0
	v_cvt_u32_f32_e32 v0, v0
	s_abs_i32 s1, s14
	s_ashr_i32 s0, s14, 31
	v_ashrrev_i32_e32 v78, 3, v76
	v_readfirstlane_b32 s16, v0
	s_mul_i32 s2, s2, s16
	s_mul_hi_u32 s2, s16, s2
	s_add_i32 s16, s16, s2
	s_mul_hi_u32 s2, s1, s16
	s_mul_i32 s2, s2, s15
	s_sub_i32 s1, s1, s2
	s_sub_i32 s2, s1, s15
	s_cmp_ge_u32 s1, s15
	s_cselect_b32 s1, s2, s1
	s_sub_i32 s2, s1, s15
	s_cmp_ge_u32 s1, s15
	s_cselect_b32 s1, s2, s1
	s_xor_b32 s1, s1, s0
	v_lshlrev_b32_e32 v2, 3, v76
	s_sub_i32 s17, s1, s0
	v_ashrrev_i32_e32 v77, 4, v76
	v_mov_b32_e32 v1, 0
	v_lshl_add_u32 v79, v82, 2, 0
	v_and_b32_e32 v80, 56, v2
	s_cmpk_lt_i32 s17, 0x480
	v_lshl_add_u32 v81, v78, 2, 0
	s_load_dword s59, s[90:91], 0xd8
	v_mbcnt_lo_u32_b32 v100, -1, 0
	v_mbcnt_hi_u32_b32 v100, -1, v100
	s_lshr_b32 s69, s94, 6
	s_lshl_b32 s82, s69, 10
	s_lshl_b32 s83, s69, 1
	s_lshr_b32 s98, s69, 2
	v_lshrrev_b32_e32 v101, 5, v100
	v_and_b32_e32 v113, 31, v100
	s_add_i32 s70, s83, 0
	v_add_u32_e32 v102, s70, v101
	s_add_i32 s70, s98, 0
	v_xor_b32_e32 v106, s70, v113
	v_lshlrev_b32_e32 v106, 4, v106
	s_add_i32 s70, s83, 16
	v_add_u32_e32 v103, s70, v101
	s_add_i32 s70, s98, 2
	v_xor_b32_e32 v107, s70, v113
	v_lshlrev_b32_e32 v107, 4, v107
	s_add_i32 s70, s83, 32
	v_add_u32_e32 v104, s70, v101
	s_add_i32 s70, s98, 4
	v_xor_b32_e32 v108, s70, v113
	v_lshlrev_b32_e32 v108, 4, v108
	s_add_i32 s70, s83, 48
	v_add_u32_e32 v105, s70, v101
	s_add_i32 s70, s98, 6
	v_xor_b32_e32 v109, s70, v113
	v_lshlrev_b32_e32 v109, 4, v109
	s_lshr_b32 s70, s94, 3
	v_lshrrev_b32_e32 v112, 3, v100
	v_add_u32_e32 v112, s70, v112
	v_and_b32_e32 v101, 7, v100
	v_lshlrev_b32_e32 v111, 4, v101
	v_lshrrev_b32_e32 v113, 2, v112
	v_xor_b32_e32 v113, v113, v101
	v_lshlrev_b32_e32 v113, 4, v113
	v_lshl_add_u32 v110, v101, 12, v113
	v_and_b32_e32 v113, 3, v112
	v_lshl_add_u32 v110, v113, 2, v110
	s_waitcnt lgkmcnt(0)
	s_add_u32 s61, s88, 0
	s_mov_b32 s101, 4160
	s_cmp_eq_u32 s59, 256
	s_cbranch_scc1 .Lwp0_gridok
	s_mov_b32 s61, s88
	s_mov_b32 s101, 7520

.LBB0_290:
	s_barrier
	s_cmp_lt_u32 s88, 200
	s_cbranch_scc1 .Lwph2_skip
	s_load_dword s59, s[90:91], 0xd8
	v_mbcnt_lo_u32_b32 v100, -1, 0
	v_mbcnt_hi_u32_b32 v100, -1, v100
	s_lshr_b32 s69, s94, 6
	s_lshl_b32 s82, s69, 10
	s_lshl_b32 s83, s69, 1
	s_lshr_b32 s98, s69, 2
	v_lshrrev_b32_e32 v101, 5, v100
	v_and_b32_e32 v113, 31, v100
	s_add_i32 s70, s83, 0
	v_add_u32_e32 v102, s70, v101
	s_add_i32 s70, s98, 0
	v_xor_b32_e32 v106, s70, v113
	v_lshlrev_b32_e32 v106, 4, v106
	s_add_i32 s70, s83, 16
	v_add_u32_e32 v103, s70, v101
	s_add_i32 s70, s98, 2
	v_xor_b32_e32 v107, s70, v113
	v_lshlrev_b32_e32 v107, 4, v107
	s_add_i32 s70, s83, 32
	v_add_u32_e32 v104, s70, v101
	s_add_i32 s70, s98, 4
	v_xor_b32_e32 v108, s70, v113
	v_lshlrev_b32_e32 v108, 4, v108
	s_add_i32 s70, s83, 48
	v_add_u32_e32 v105, s70, v101
	s_add_i32 s70, s98, 6
	v_xor_b32_e32 v109, s70, v113
	v_lshlrev_b32_e32 v109, 4, v109
	s_lshr_b32 s70, s94, 3
	v_lshrrev_b32_e32 v112, 3, v100
	v_add_u32_e32 v112, s70, v112
	v_and_b32_e32 v101, 7, v100
	v_lshlrev_b32_e32 v111, 4, v101
	v_lshrrev_b32_e32 v113, 2, v112
	v_xor_b32_e32 v113, v113, v101
	v_lshlrev_b32_e32 v113, 4, v113
	v_lshl_add_u32 v110, v101, 12, v113
	v_and_b32_e32 v113, 3, v112
	v_lshl_add_u32 v110, v113, 2, v110
	s_waitcnt lgkmcnt(0)
	s_cmp_lg_u32 s59, 256
	s_cbranch_scc1 .Lwph2_end
	s_sub_u32 s61, s88, 200
	s_add_u32 s61, s61, 4160
	s_mov_b32 s59, 56
	s_mov_b32 s101, 6400
	s_mov_b32 s60, s61
	s_mov_b32 s58, -2

.LBB0_646:
	s_barrier
	s_cmp_lt_u32 s88, 128
	s_cbranch_scc1 .Lwph7_skip
	s_load_dword s59, s[90:91], 0xd8
	v_mbcnt_lo_u32_b32 v100, -1, 0
	v_mbcnt_hi_u32_b32 v100, -1, v100
	s_lshr_b32 s69, s94, 6
	s_lshl_b32 s82, s69, 10
	s_lshl_b32 s83, s69, 1
	s_lshr_b32 s98, s69, 2
	v_lshrrev_b32_e32 v101, 5, v100
	v_and_b32_e32 v113, 31, v100
	s_add_i32 s70, s83, 0
	v_add_u32_e32 v102, s70, v101
	s_add_i32 s70, s98, 0
	v_xor_b32_e32 v106, s70, v113
	v_lshlrev_b32_e32 v106, 4, v106
	s_add_i32 s70, s83, 16
	v_add_u32_e32 v103, s70, v101
	s_add_i32 s70, s98, 2
	v_xor_b32_e32 v107, s70, v113
	v_lshlrev_b32_e32 v107, 4, v107
	s_add_i32 s70, s83, 32
	v_add_u32_e32 v104, s70, v101
	s_add_i32 s70, s98, 4
	v_xor_b32_e32 v108, s70, v113
	v_lshlrev_b32_e32 v108, 4, v108
	s_add_i32 s70, s83, 48
	v_add_u32_e32 v105, s70, v101
	s_add_i32 s70, s98, 6
	v_xor_b32_e32 v109, s70, v113
	v_lshlrev_b32_e32 v109, 4, v109
	s_lshr_b32 s70, s94, 3
	v_lshrrev_b32_e32 v112, 3, v100
	v_add_u32_e32 v112, s70, v112
	v_and_b32_e32 v101, 7, v100
	v_lshlrev_b32_e32 v111, 4, v101
	v_lshrrev_b32_e32 v113, 2, v112
	v_xor_b32_e32 v113, v113, v101
	v_lshlrev_b32_e32 v113, 4, v113
	v_lshl_add_u32 v110, v101, 12, v113
	v_and_b32_e32 v113, 3, v112
	v_lshl_add_u32 v110, v113, 2, v110
	s_waitcnt lgkmcnt(0)
	s_cmp_lg_u32 s59, 256
	s_cbranch_scc1 .Lwph7_end
	s_sub_u32 s61, s88, 128
	s_add_u32 s61, s61, 6400
	s_mov_b32 s59, 128
	s_mov_b32 s101, 6784
	s_mov_b32 s60, s61
	s_mov_b32 s58, -2

.Lwph7_skip:
.LBB0_647:
	s_cmp_lt_i32 s92, 9
	s_cselect_b64 s[6:7], -1, 0
	s_cmp_gt_i32 s92, 8
	s_cselect_b64 s[0:1], -1, 0
	s_cmp_lt_i32 s93, 9
	s_cselect_b64 s[2:3], -1, 0
	s_or_b64 s[0:1], s[0:1], s[2:3]
	s_and_b64 vcc, exec, s[0:1]
	s_cbranch_vccnz .LBB0_685
	s_andn2_b64 vcc, exec, s[8:9]
	s_cbranch_vccnz .LBB0_659
	s_waitcnt vmcnt(0)
	v_readlane_b32 s0, v245, 32
	v_readlane_b32 s1, v245, 33
	s_add_i32 s95, s95, 1
	s_andn2_b64 vcc, exec, s[0:1]
	s_waitcnt vmcnt(0) lgkmcnt(0)
	s_barrier
	s_cbranch_vccnz .LBB0_658
	v_mbcnt_lo_u32_b32 v0, -1, 0
	v_mbcnt_hi_u32_b32 v0, -1, v0
	v_cmp_eq_u32_e32 vcc, 0, v0
	s_and_saveexec_b64 s[2:3], vcc
	s_cbranch_execz .LBB0_657
	v_readlane_b32 s0, v245, 50
	s_lshl_b32 s0, s0, 8
	s_add_u32 s0, s96, s0
	s_addc_u32 s1, s97, 0
	v_mov_b32_e32 v0, 0x1000
	v_mov_b32_e32 v1, 1
	global_atomic_add v0, v0, v1, s[0:1] sc0
	v_readlane_b32 s0, v245, 51
	s_add_u32 s4, s86, 0x4b500
	s_mul_i32 s0, s95, s0
	s_addc_u32 s5, s87, 0
	s_waitcnt vmcnt(0)
	v_add_u32_e32 v0, 1, v0
	v_cmp_eq_u32_e32 vcc, s0, v0
	s_and_saveexec_b64 s[8:9], vcc
	s_cbranch_execz .LBB0_654
	s_mov_b64 s[10:11], exec
	v_mbcnt_lo_u32_b32 v0, s10, 0
	buffer_wbl2 sc1
	s_waitcnt vmcnt(0)
	v_mbcnt_hi_u32_b32 v0, s11, v0
	v_cmp_eq_u32_e32 vcc, 0, v0
	s_and_b64 s[0:1], exec, vcc
	s_mov_b64 exec, s[0:1]
	s_cbranch_execz .LBB0_654
	s_bcnt1_i32_b64 s0, s[10:11]
	v_mov_b32_e32 v0, 0
	v_mov_b32_e32 v1, s0
	global_atomic_add v0, v1, s[4:5]

.LBB0_710:
	s_barrier
	s_cmp_lt_u32 s88, 216
	s_cbranch_scc1 .Lwph9a_skip
	s_load_dword s59, s[90:91], 0xd8
	v_mbcnt_lo_u32_b32 v100, -1, 0
	v_mbcnt_hi_u32_b32 v100, -1, v100
	s_lshr_b32 s69, s94, 6
	s_lshl_b32 s82, s69, 10
	s_lshl_b32 s83, s69, 1
	s_lshr_b32 s98, s69, 2
	v_lshrrev_b32_e32 v101, 5, v100
	v_and_b32_e32 v113, 31, v100
	s_add_i32 s70, s83, 0
	v_add_u32_e32 v102, s70, v101
	s_add_i32 s70, s98, 0
	v_xor_b32_e32 v106, s70, v113
	v_lshlrev_b32_e32 v106, 4, v106
	s_add_i32 s70, s83, 16
	v_add_u32_e32 v103, s70, v101
	s_add_i32 s70, s98, 2
	v_xor_b32_e32 v107, s70, v113
	v_lshlrev_b32_e32 v107, 4, v107
	s_add_i32 s70, s83, 32
	v_add_u32_e32 v104, s70, v101
	s_add_i32 s70, s98, 4
	v_xor_b32_e32 v108, s70, v113
	v_lshlrev_b32_e32 v108, 4, v108
	s_add_i32 s70, s83, 48
	v_add_u32_e32 v105, s70, v101
	s_add_i32 s70, s98, 6
	v_xor_b32_e32 v109, s70, v113
	v_lshlrev_b32_e32 v109, 4, v109
	s_lshr_b32 s70, s94, 3
	v_lshrrev_b32_e32 v112, 3, v100
	v_add_u32_e32 v112, s70, v112
	v_and_b32_e32 v101, 7, v100
	v_lshlrev_b32_e32 v111, 4, v101
	v_lshrrev_b32_e32 v113, 2, v112
	v_xor_b32_e32 v113, v113, v101
	v_lshlrev_b32_e32 v113, 4, v113
	v_lshl_add_u32 v110, v101, 12, v113
	v_and_b32_e32 v113, 3, v112
	v_lshl_add_u32 v110, v113, 2, v110
	s_waitcnt lgkmcnt(0)
	s_cmp_lg_u32 s59, 256
	s_cbranch_scc1 .Lwph9a_end
	s_sub_u32 s61, s88, 216
	s_add_u32 s61, s61, 768
	s_mov_b32 s59, 40
	s_mov_b32 s101, 1632
	s_mov_b32 s60, s61
	s_mov_b32 s58, -2

.Lwph9a_skip:
	s_cmp_lt_u32 s88, 216
	s_cbranch_scc1 .Lwph9b_skip
	s_load_dword s59, s[90:91], 0xd8
	v_mbcnt_lo_u32_b32 v100, -1, 0
	v_mbcnt_hi_u32_b32 v100, -1, v100
	s_lshr_b32 s69, s94, 6
	s_lshl_b32 s82, s69, 10
	s_lshl_b32 s83, s69, 1
	s_lshr_b32 s98, s69, 2
	v_lshrrev_b32_e32 v101, 5, v100
	v_and_b32_e32 v113, 31, v100
	s_add_i32 s70, s83, 0
	v_add_u32_e32 v102, s70, v101
	s_add_i32 s70, s98, 0
	v_xor_b32_e32 v106, s70, v113
	v_lshlrev_b32_e32 v106, 4, v106
	s_add_i32 s70, s83, 16
	v_add_u32_e32 v103, s70, v101
	s_add_i32 s70, s98, 2
	v_xor_b32_e32 v107, s70, v113
	v_lshlrev_b32_e32 v107, 4, v107
	s_add_i32 s70, s83, 32
	v_add_u32_e32 v104, s70, v101
	s_add_i32 s70, s98, 4
	v_xor_b32_e32 v108, s70, v113
	v_lshlrev_b32_e32 v108, 4, v108
	s_add_i32 s70, s83, 48
	v_add_u32_e32 v105, s70, v101
	s_add_i32 s70, s98, 6
	v_xor_b32_e32 v109, s70, v113
	v_lshlrev_b32_e32 v109, 4, v109
	s_lshr_b32 s70, s94, 3
	v_lshrrev_b32_e32 v112, 3, v100
	v_add_u32_e32 v112, s70, v112
	v_and_b32_e32 v101, 7, v100
	v_lshlrev_b32_e32 v111, 4, v101
	v_lshrrev_b32_e32 v113, 2, v112
	v_xor_b32_e32 v113, v113, v101
	v_lshlrev_b32_e32 v113, 4, v113
	v_lshl_add_u32 v110, v101, 12, v113
	v_and_b32_e32 v113, 3, v112
	v_lshl_add_u32 v110, v113, 2, v110
	s_waitcnt lgkmcnt(0)
	s_cmp_lg_u32 s59, 256
	s_cbranch_scc1 .Lwph9b_end
	s_sub_u32 s61, s88, 216
	s_add_u32 s61, s61, 6784
	s_mov_b32 s59, 40
	s_mov_b32 s101, 7520
	s_mov_b32 s60, s61
	s_mov_b32 s58, -2

.LBB0_771:
	s_barrier
	s_cmp_lt_u32 s88, 176
	s_cbranch_scc1 .Lwph10_skip
	s_load_dword s59, s[90:91], 0xd8
	v_mbcnt_lo_u32_b32 v100, -1, 0
	v_mbcnt_hi_u32_b32 v100, -1, v100
	s_lshr_b32 s69, s94, 6
	s_lshl_b32 s82, s69, 10
	s_lshl_b32 s83, s69, 1
	s_lshr_b32 s98, s69, 2
	v_lshrrev_b32_e32 v101, 5, v100
	v_and_b32_e32 v113, 31, v100
	s_add_i32 s70, s83, 0
	v_add_u32_e32 v102, s70, v101
	s_add_i32 s70, s98, 0
	v_xor_b32_e32 v106, s70, v113
	v_lshlrev_b32_e32 v106, 4, v106
	s_add_i32 s70, s83, 16
	v_add_u32_e32 v103, s70, v101
	s_add_i32 s70, s98, 2
	v_xor_b32_e32 v107, s70, v113
	v_lshlrev_b32_e32 v107, 4, v107
	s_add_i32 s70, s83, 32
	v_add_u32_e32 v104, s70, v101
	s_add_i32 s70, s98, 4
	v_xor_b32_e32 v108, s70, v113
	v_lshlrev_b32_e32 v108, 4, v108
	s_add_i32 s70, s83, 48
	v_add_u32_e32 v105, s70, v101
	s_add_i32 s70, s98, 6
	v_xor_b32_e32 v109, s70, v113
	v_lshlrev_b32_e32 v109, 4, v109
	s_lshr_b32 s70, s94, 3
	v_lshrrev_b32_e32 v112, 3, v100
	v_add_u32_e32 v112, s70, v112
	v_and_b32_e32 v101, 7, v100
	v_lshlrev_b32_e32 v111, 4, v101
	v_lshrrev_b32_e32 v113, 2, v112
	v_xor_b32_e32 v113, v113, v101
	v_lshlrev_b32_e32 v113, 4, v113
	v_lshl_add_u32 v110, v101, 12, v113
	v_and_b32_e32 v113, 3, v112
	v_lshl_add_u32 v110, v113, 2, v110
	s_waitcnt lgkmcnt(0)
	s_cmp_lg_u32 s59, 256
	s_cbranch_scc1 .Lwph10_end
	s_sub_u32 s61, s88, 176
	s_add_u32 s61, s61, 1632
	s_mov_b32 s59, 80
	s_mov_b32 s101, 2272
	s_mov_b32 s60, s61
	s_mov_b32 s58, -2

.LBB0_784:
	s_mov_b64 s[4:5], 0
	s_load_dword s12, s[90:91], 0xd8
	v_mbcnt_lo_u32_b32 v0, -1, 0
	v_mbcnt_hi_u32_b32 v77, -1, v0
	v_or_b32_e32 v76, s94, v77
	s_mov_b32 s0, s88
	s_add_u32 s8, s86, s4
	s_waitcnt lgkmcnt(0)
	s_mov_b32 s1, s12
	v_mov_b32_e32 v78, v76
	s_mov_b32 s13, s12
	s_addc_u32 s9, s87, s5
	s_abs_i32 s22, s13
	v_cvt_f32_u32_e32 v2, s22
	v_lshlrev_b32_e32 v0, 2, v78
	v_and_b32_e32 v84, 60, v0
	s_sub_i32 s2, 0, s22
	v_rcp_iflag_f32_e32 v0, v2
	s_mov_b32 s14, s88
	s_add_i32 s15, s14, s13
	v_mul_f32_e32 v0, 0x4f7ffffe, v0
	v_cvt_u32_f32_e32 v0, v0
	s_abs_i32 s1, s15
	s_ashr_i32 s0, s15, 31
	v_ashrrev_i32_e32 v80, 3, v78
	v_readfirstlane_b32 s23, v0
	s_mul_i32 s2, s2, s23
	s_mul_hi_u32 s2, s23, s2
	s_add_i32 s23, s23, s2
	s_mul_hi_u32 s2, s1, s23
	s_mul_i32 s2, s2, s22
	s_sub_i32 s1, s1, s2
	s_sub_i32 s2, s1, s22
	s_cmp_ge_u32 s1, s22
	s_cselect_b32 s1, s2, s1
	s_sub_i32 s2, s1, s22
	s_cmp_ge_u32 s1, s22
	s_cselect_b32 s1, s2, s1
	s_xor_b32 s1, s1, s0
	v_lshlrev_b32_e32 v2, 3, v78
	s_sub_i32 s24, s1, s0
	v_ashrrev_i32_e32 v79, 4, v78
	v_mov_b32_e32 v1, 0
	v_lshl_add_u32 v81, v84, 2, 0
	v_and_b32_e32 v82, 56, v2
	s_cmpk_lt_i32 s24, 0x480
	v_lshl_add_u32 v83, v80, 2, 0
	s_load_dword s59, s[90:91], 0xd8
	v_mbcnt_lo_u32_b32 v100, -1, 0
	v_mbcnt_hi_u32_b32 v100, -1, v100
	s_lshr_b32 s69, s94, 6
	s_lshl_b32 s82, s69, 10
	s_lshl_b32 s83, s69, 1
	s_lshr_b32 s98, s69, 2
	v_lshrrev_b32_e32 v101, 5, v100
	v_and_b32_e32 v113, 31, v100
	s_add_i32 s70, s83, 0
	v_add_u32_e32 v102, s70, v101
	s_add_i32 s70, s98, 0
	v_xor_b32_e32 v106, s70, v113
	v_lshlrev_b32_e32 v106, 4, v106
	s_add_i32 s70, s83, 16
	v_add_u32_e32 v103, s70, v101
	s_add_i32 s70, s98, 2
	v_xor_b32_e32 v107, s70, v113
	v_lshlrev_b32_e32 v107, 4, v107
	s_add_i32 s70, s83, 32
	v_add_u32_e32 v104, s70, v101
	s_add_i32 s70, s98, 4
	v_xor_b32_e32 v108, s70, v113
	v_lshlrev_b32_e32 v108, 4, v108
	s_add_i32 s70, s83, 48
	v_add_u32_e32 v105, s70, v101
	s_add_i32 s70, s98, 6
	v_xor_b32_e32 v109, s70, v113
	v_lshlrev_b32_e32 v109, 4, v109
	s_lshr_b32 s70, s94, 3
	v_lshrrev_b32_e32 v112, 3, v100
	v_add_u32_e32 v112, s70, v112
	v_and_b32_e32 v101, 7, v100
	v_lshlrev_b32_e32 v111, 4, v101
	v_lshrrev_b32_e32 v113, 2, v112
	v_xor_b32_e32 v113, v113, v101
	v_lshlrev_b32_e32 v113, 4, v113
	v_lshl_add_u32 v110, v101, 12, v113
	v_and_b32_e32 v113, 3, v112
	v_lshl_add_u32 v110, v113, 2, v110
	s_waitcnt lgkmcnt(0)
	s_add_u32 s61, s88, 2272
	s_mov_b32 s101, 2272
	s_cmp_eq_u32 s59, 256
	s_cbranch_scc1 .Lwp1_gridok
	s_mov_b32 s61, s88
	s_mov_b32 s101, 7520

.LBB0_966:
	s_barrier
	s_cmp_lt_u32 s88, 132
	s_cbranch_scc1 .Lwph12_skip
	s_load_dword s59, s[90:91], 0xd8
	v_mbcnt_lo_u32_b32 v100, -1, 0
	v_mbcnt_hi_u32_b32 v100, -1, v100
	s_lshr_b32 s69, s94, 6
	s_lshl_b32 s82, s69, 10
	s_lshl_b32 s83, s69, 1
	s_lshr_b32 s98, s69, 2
	v_lshrrev_b32_e32 v101, 5, v100
	v_and_b32_e32 v113, 31, v100
	s_add_i32 s70, s83, 0
	v_add_u32_e32 v102, s70, v101
	s_add_i32 s70, s98, 0
	v_xor_b32_e32 v106, s70, v113
	v_lshlrev_b32_e32 v106, 4, v106
	s_add_i32 s70, s83, 16
	v_add_u32_e32 v103, s70, v101
	s_add_i32 s70, s98, 2
	v_xor_b32_e32 v107, s70, v113
	v_lshlrev_b32_e32 v107, 4, v107
	s_add_i32 s70, s83, 32
	v_add_u32_e32 v104, s70, v101
	s_add_i32 s70, s98, 4
	v_xor_b32_e32 v108, s70, v113
	v_lshlrev_b32_e32 v108, 4, v108
	s_add_i32 s70, s83, 48
	v_add_u32_e32 v105, s70, v101
	s_add_i32 s70, s98, 6
	v_xor_b32_e32 v109, s70, v113
	v_lshlrev_b32_e32 v109, 4, v109
	s_lshr_b32 s70, s94, 3
	v_lshrrev_b32_e32 v112, 3, v100
	v_add_u32_e32 v112, s70, v112
	v_and_b32_e32 v101, 7, v100
	v_lshlrev_b32_e32 v111, 4, v101
	v_lshrrev_b32_e32 v113, 2, v112
	v_xor_b32_e32 v113, v113, v101
	v_lshlrev_b32_e32 v113, 4, v113
	v_lshl_add_u32 v110, v101, 12, v113
	v_and_b32_e32 v113, 3, v112
	v_lshl_add_u32 v110, v113, 2, v110
	s_waitcnt lgkmcnt(0)
	s_cmp_lg_u32 s59, 256
	s_cbranch_scc1 .Lwph12_end
	s_sub_u32 s61, s88, 132
	s_add_u32 s61, s61, 2272
	s_mov_b32 s59, 124
	s_mov_b32 s101, 6112
	s_mov_b32 s60, s61
	s_mov_b32 s58, -2

.LBB0_1249:
	s_barrier
	s_cmp_lt_u32 s88, 128
	s_cbranch_scc1 .Lwph19_skip
	s_load_dword s59, s[90:91], 0xd8
	v_mbcnt_lo_u32_b32 v100, -1, 0
	v_mbcnt_hi_u32_b32 v100, -1, v100
	s_lshr_b32 s69, s94, 6
	s_lshl_b32 s82, s69, 10
	s_lshl_b32 s83, s69, 1
	s_lshr_b32 s98, s69, 2
	v_lshrrev_b32_e32 v101, 5, v100
	v_and_b32_e32 v113, 31, v100
	s_add_i32 s70, s83, 0
	v_add_u32_e32 v102, s70, v101
	s_add_i32 s70, s98, 0
	v_xor_b32_e32 v106, s70, v113
	v_lshlrev_b32_e32 v106, 4, v106
	s_add_i32 s70, s83, 16
	v_add_u32_e32 v103, s70, v101
	s_add_i32 s70, s98, 2
	v_xor_b32_e32 v107, s70, v113
	v_lshlrev_b32_e32 v107, 4, v107
	s_add_i32 s70, s83, 32
	v_add_u32_e32 v104, s70, v101
	s_add_i32 s70, s98, 4
	v_xor_b32_e32 v108, s70, v113
	v_lshlrev_b32_e32 v108, 4, v108
	s_add_i32 s70, s83, 48
	v_add_u32_e32 v105, s70, v101
	s_add_i32 s70, s98, 6
	v_xor_b32_e32 v109, s70, v113
	v_lshlrev_b32_e32 v109, 4, v109
	s_lshr_b32 s70, s94, 3
	v_lshrrev_b32_e32 v112, 3, v100
	v_add_u32_e32 v112, s70, v112
	v_and_b32_e32 v101, 7, v100
	v_lshlrev_b32_e32 v111, 4, v101
	v_lshrrev_b32_e32 v113, 2, v112
	v_xor_b32_e32 v113, v113, v101
	v_lshlrev_b32_e32 v113, 4, v113
	v_lshl_add_u32 v110, v101, 12, v113
	v_and_b32_e32 v113, 3, v112
	v_lshl_add_u32 v110, v113, 2, v110
	s_waitcnt lgkmcnt(0)
	s_cmp_lg_u32 s59, 256
	s_cbranch_scc1 .Lwph19_end
	s_sub_u32 s61, s88, 128
	s_add_u32 s61, s61, 6112
	s_mov_b32 s59, 128
	s_mov_b32 s101, 7520
	s_mov_b32 s60, s61
	s_mov_b32 s58, -2

.Lwph19_skip:
.LBB0_1250:
	s_cmp_gt_i32 s92, 20
	s_cselect_b64 s[0:1], -1, 0
	s_cmp_lt_i32 s93, 21
	s_cselect_b64 s[4:5], -1, 0
	s_or_b64 s[0:1], s[0:1], s[4:5]
	s_and_b64 vcc, exec, s[0:1]
	s_cbranch_vccnz .LBB0_1284
	s_andn2_b64 vcc, exec, s[2:3]
	s_cbranch_vccnz .LBB0_1262
	s_waitcnt vmcnt(0)
	v_readlane_b32 s0, v245, 32
	v_readlane_b32 s1, v245, 33
	s_andn2_b64 vcc, exec, s[0:1]
	s_waitcnt vmcnt(0) lgkmcnt(0)
	s_barrier
	s_cbranch_vccnz .LBB0_1261
	v_mbcnt_lo_u32_b32 v0, -1, 0
	v_mbcnt_hi_u32_b32 v0, -1, v0
	v_cmp_eq_u32_e32 vcc, 0, v0
	s_and_saveexec_b64 s[2:3], vcc
	s_cbranch_execz .LBB0_1260
	v_readlane_b32 s1, v245, 50
	s_add_i32 s0, s95, 1
	s_lshl_b32 s1, s1, 8
	s_add_u32 s4, s96, s1
	s_addc_u32 s5, s97, 0
	v_mov_b32_e32 v0, 0x1000
	v_mov_b32_e32 v1, 1
	global_atomic_add v0, v0, v1, s[4:5] sc0
	v_readlane_b32 s1, v245, 51
	s_add_u32 s4, s86, 0x4b500
	s_mul_i32 s1, s0, s1
	s_addc_u32 s5, s87, 0
	s_waitcnt vmcnt(0)
	v_add_u32_e32 v0, 1, v0
	v_cmp_eq_u32_e32 vcc, s1, v0
	s_and_saveexec_b64 s[6:7], vcc
	s_cbranch_execz .LBB0_1257
	s_mov_b64 s[8:9], exec
	v_mbcnt_lo_u32_b32 v0, s8, 0
	buffer_wbl2 sc1
	s_waitcnt vmcnt(0)
	v_mbcnt_hi_u32_b32 v0, s9, v0
	v_cmp_eq_u32_e32 vcc, 0, v0
	s_and_b64 s[10:11], exec, vcc
	s_mov_b64 exec, s[10:11]
	s_cbranch_execz .LBB0_1257
	s_bcnt1_i32_b64 s1, s[8:9]
	v_mov_b32_e32 v0, 0
	v_mov_b32_e32 v1, s1
	global_atomic_add v0, v1, s[4:5]
